# P4: residual x rows of the first three half row-groups fetched in the phase prologue (v224..v247 free across the K-loop), on top of the P6 prefetch
# baseline (speedup 1.0000x reference)
; #define PG8_STAGE(bufoff, gbase, voff) do { _Pragma("unroll") for (int _i = 0; _i < 2; ++_i) \
;         __builtin_amdgcn_global_load_lds((const unsigned*)((const char*)(gbase) + (voff)[_i]), (PG8_LAS unsigned*)(lds + (bufoff) + ldsw + _i * 8192), 16, 0, 0); } while (0)
; #define PG8_WAIT_V(n) asm volatile("s_waitcnt vmcnt(" #n ")" ::: "memory")
; #define PG8_BAR __builtin_amdgcn_s_barrier()
;     __device__ __forceinline__ void operator()(PG8_ACC, const Unit& u, int wr, int wc, int fr, int fq) const {
;     ...
;             for (int m = 0; m < 4; ++m) { const int row = row0 + ai * HALF + m * 16; const size_t off = (size_t)row * ld + col0; float s = 0.f;
; #pragma unroll
;                 for (int bj = 0; bj < 2; ++bj) {
;                     const f32x4 r0 = *(const f32x4*)(res + off + bj * HALF), r1 = *(const f32x4*)(res + off + bj * HALF + 4);
;                     const f32x4 v0 = acc[ai][bj][m][0] + r0, v1 = acc[ai][bj][m][1] + r1;
; template <class Epi, class Sched, bool ALIGN_EPI = false, bool SP2 = false>
; __device__ __forceinline__ void gemm_phase(PG8_LAS unsigned char* lds, const Gemm g, const Sched& S, const Epi& E, int wave_id) {
;     ...
;         PG8_STAGE(PG8_SB(0, 0), cB, voffB); PG8_STAGE(PG8_SB(0, 1), cB + hstepB, voffB); PG8_STAGE(PG8_SA(0, 0), cA, voffA); PG8_STAGE(PG8_SA(0, 1), cA + hstepA, voffA);
;         if (wr == 1) PG8_BAR;
;         PG8_WAIT_V(2); PG8_BAR;
;         PG8_STAGE(PG8_SB(1, 0), cB + kstep, voffB); PG8_STAGE(PG8_SA(1, 0), cA + kstep, voffA); PG8_STAGE(PG8_SB(1, 1), cB + hstepB + kstep, voffB);
;         PG8_WAIT_V(6); PG8_BAR;
.LBB0_621:
	s_lshl_b32 s5, s5, 5
	s_mov_b64 s[40:41], 0x80
	s_and_b32 s27, s5, 0x60
	s_add_i32 m0, s31, 0x18000
	v_lshl_add_u64 v[6:7], v[6:7], 0, s[40:41]
	s_lshl_b32 s26, s4, 13
	s_lshl_b32 s5, s27, 7
	s_waitcnt vmcnt(2)
	s_barrier
	global_load_lds_dwordx4 v[6:7], off
	v_lshl_add_u64 v[4:5], v[4:5], 0, s[40:41]
	s_add_i32 m0, s31, 0x1a000
	s_add_i32 s60, s31, 0x8000
	s_add_i32 s61, s31, 0xa000
	global_load_lds_dwordx4 v[4:5], off
	v_lshl_add_u64 v[0:1], v[0:1], 0, s[40:41]
	s_mov_b32 m0, s60
	s_add_u32 s8, s54, 0x40080
	global_load_lds_dwordx4 v[0:1], off
	v_lshl_add_u64 v[0:1], v[2:3], 0, s[40:41]
	s_mov_b32 m0, s61
	s_addc_u32 s9, s55, 0
	global_load_lds_dwordx4 v[0:1], off
	s_add_i32 m0, s31, 0x1c000
	v_lshl_add_u64 v[0:1], s[8:9], 0, v[146:147]
	global_load_lds_dwordx4 v[0:1], off
	v_lshl_add_u64 v[0:1], s[8:9], 0, v[150:151]
	s_add_i32 m0, s31, 0x1e000
	s_cmpk_lt_u32 s6, 0x100
	global_load_lds_dwordx4 v[0:1], off
	v_bfe_u32 v0, v8, 4, 2
	v_and_b32_e32 v1, 15, v8
	v_lshlrev_b32_e32 v2, 4, v0
	v_lshl_or_b32 v164, s4, 6, v1
	v_lshl_or_b32 v1, v1, 6, v2
	v_lshlrev_b32_e32 v2, 2, v8
	v_and_b32_e32 v2, 32, v2
	v_bitop3_b32 v3, v1, s26, v2 bitop3:0xde
	v_bitop3_b32 v165, v1, s5, v2 bitop3:0xde
	s_mov_b32 s26, 0x1a000
	v_cmp_eq_u32_e64 s[4:5], 0, v0
	v_lshl_or_b32 v166, v0, 3, s27
	v_lshrrev_b32_e32 v1, 1, v9
	v_mul_lo_u32 v0, v10, s7
	v_mad_u64_u32 v[0:1], s[8:9], v1, s26, v[0:1]
	v_or_b32_e32 v0, v0, v11
	v_add_lshl_u32 v0, v0, v12, 1
	v_mov_b32_e32 v1, v147
	s_mov_b64 s[8:9], 0x1a0080
	v_lshl_add_u64 v[152:153], v[0:1], 0, s[8:9]
	v_lshrrev_b32_e32 v1, 1, v13
	v_mul_lo_u32 v0, v14, s7
	v_mad_u64_u32 v[0:1], s[6:7], v1, s26, v[0:1]
	s_waitcnt vmcnt(6)
	v_or_b32_e32 v0, v0, v15
	s_cselect_b64 s[42:43], -1, 0
	v_add_lshl_u32 v0, v0, v16, 1
	v_mov_b32_e32 v1, v147
	s_add_i32 s64, 0, 0x10000
	s_add_i32 s65, 0, 0x14000
	s_mov_b32 s62, s24
	s_ashr_i32 s63, s2, 31
	v_lshl_add_u64 v[154:155], v[0:1], 0, s[8:9]
	v_mov_b64_e32 v[156:157], 0x100
	v_mov_b64_e32 v[158:159], 0xff
	v_add_u32_e32 v167, s64, v165
	v_add_u32_e32 v168, s65, v165
	v_add_u32_e32 v169, 0, v3
	s_movk_i32 s66, 0x3400
	v_lshl_add_u32 v252, s68, 8, v164
	v_lshl_or_b32 v250, s50, 8, v166
	v_ashrrev_i32_e32 v253, 31, v252
	v_ashrrev_i32_e32 v251, 31, v250
	v_lshlrev_b64 v[252:253], 10, v[252:253]
	v_lshl_add_u64 v[252:253], v[252:253], 0, v[250:251]
	v_lshlrev_b64 v[252:253], 2, v[252:253]
	v_lshl_add_u64 v[252:253], s[16:17], 0, v[252:253]
	s_mov_b64 s[100:101], 0x10000
	global_load_dwordx4 v[224:227], v[252:253], off
	global_load_dwordx4 v[228:231], v[252:253], off offset:16
	global_load_dwordx4 v[232:235], v[252:253], off offset:512
	global_load_dwordx4 v[236:239], v[252:253], off offset:528
	v_lshl_add_u64 v[252:253], v[252:253], 0, s[100:101]
	global_load_dwordx4 v[240:243], v[252:253], off
	global_load_dwordx4 v[244:247], v[252:253], off offset:16
	s_barrier
	s_branch .LBB0_624

; __device__ __forceinline__ unsigned cvt_pk_bf16(float lo, float hi) { f32x2v_t v = {lo, hi}; bf16x2v_t b = __builtin_convertvector(v, bf16x2v_t); return __builtin_bit_cast(unsigned, b); }
;     __device__ __forceinline__ void operator()(PG8_ACC, const Unit& u, int wr, int wc, int fr, int fq) const {
;     ...
;         for (int ai = 0; ai < 2; ++ai)
; #pragma unroll
;             for (int m = 0; m < 4; ++m) { const int row = row0 + ai * HALF + m * 16; const size_t off = (size_t)row * ld + col0; float s = 0.f;
; #pragma unroll
;                 for (int bj = 0; bj < 2; ++bj) {
;                     const f32x4 r0 = *(const f32x4*)(res + off + bj * HALF), r1 = *(const f32x4*)(res + off + bj * HALF + 4);
;                     const f32x4 v0 = acc[ai][bj][m][0] + r0, v1 = acc[ai][bj][m][1] + r1;
;                     *(f32x4*)(out + off + bj * HALF) = v0; *(f32x4*)(out + off + bj * HALF + 4) = v1;
;                     s += (v0[0] * v0[0] + v0[1] * v0[1]) + (v0[2] * v0[2] + v0[3] * v0[3]) + (v1[0] * v1[0] + v1[1] * v1[1]) + (v1[2] * v1[2] + v1[3] * v1[3]);
;                     const f32x4 h0 = v0 * gv[bj][0], h1 = v1 * gv[bj][1];
;                     u32x4 w; w.x = cvt_pk_bf16(h0[0], h0[1]); w.y = cvt_pk_bf16(h0[2], h0[3]); w.z = cvt_pk_bf16(h1[0], h1[1]); w.w = cvt_pk_bf16(h1[2], h1[3]);
;                     *(u32x4*)(H + (size_t)row * ldh + col0 + bj * HALF) = w; }
;                 s += shx<16>(s); s = sum_halves(s);
;                 if (fq == 0) atomicAdd(SSQ + row, s); }
.LBB0_636:
	v_lshl_add_u32 v162, s68, 8, v164
	v_lshl_or_b32 v160, s50, 8, v166
	v_ashrrev_i32_e32 v163, 31, v162
	v_ashrrev_i32_e32 v161, 31, v160
	v_lshlrev_b64 v[80:81], 10, v[162:163]
	v_lshl_add_u64 v[80:81], v[80:81], 0, v[160:161]
	v_lshlrev_b64 v[178:179], 2, v[80:81]
	v_lshl_add_u64 v[180:181], s[16:17], 0, v[178:179]
	v_lshl_add_u64 v[84:85], v[160:161], 2, s[22:23]
	global_load_dwordx4 v[92:95], v[84:85], off
	global_load_dwordx4 v[88:91], v[84:85], off offset:16
	v_mov_b64_e32 v[80:81], s[18:19]
	v_mad_i64_i32 v[80:81], s[8:9], v162, s66, v[80:81]
	v_lshl_add_u64 v[182:183], v[160:161], 1, v[80:81]
	v_lshl_add_u64 v[178:179], s[12:13], 0, v[178:179]
	global_load_dwordx4 v[80:83], v[84:85], off offset:528
	s_nop 0
	global_load_dwordx4 v[84:87], v[84:85], off offset:512
	s_waitcnt vmcnt(0)
	v_pk_add_f32 v[142:143], v[142:143], v[226:227]
	v_pk_add_f32 v[140:141], v[140:141], v[224:225]
	v_pk_add_f32 v[138:139], v[138:139], v[230:231]
	v_pk_add_f32 v[136:137], v[136:137], v[228:229]
	v_pk_mul_f32 v[172:173], v[94:95], v[142:143]
	v_pk_mul_f32 v[170:171], v[92:93], v[140:141]
	v_pk_mul_f32 v[174:175], v[90:91], v[138:139]
	v_pk_mul_f32 v[176:177], v[88:89], v[136:137]
	v_cvt_pk_bf16_f32 v170, v170, v171
	v_cvt_pk_bf16_f32 v171, v172, v173
	v_cvt_pk_bf16_f32 v172, v176, v177
	v_cvt_pk_bf16_f32 v173, v174, v175
	global_store_dwordx4 v[178:179], v[140:143], off
	global_store_dwordx4 v[178:179], v[136:139], off offset:16
	global_store_dwordx4 v[182:183], v[170:173], off
	v_mul_f32_e32 v141, v141, v141
	v_mul_f32_e32 v143, v143, v143
	v_mul_f32_e32 v137, v137, v137
	v_fmac_f32_e32 v141, v140, v140
	v_fmac_f32_e32 v143, v142, v142
	v_mul_f32_e32 v139, v139, v139
	v_fmac_f32_e32 v137, v136, v136
	v_add_f32_e32 v136, v141, v143
	v_fmac_f32_e32 v139, v138, v138
	v_add_f32_e32 v136, v136, v137
	v_add_f32_e32 v180, v139, v136
	v_pk_add_f32 v[134:135], v[134:135], v[234:235]
	v_pk_add_f32 v[132:133], v[132:133], v[232:233]
	v_pk_add_f32 v[128:129], v[128:129], v[236:237]
	v_mul_f32_e32 v170, v133, v133
	v_mul_f32_e32 v171, v135, v135
	v_pk_add_f32 v[130:131], v[130:131], v[238:239]
	v_mul_f32_e32 v172, v129, v129
	v_fmac_f32_e32 v170, v132, v132
	v_fmac_f32_e32 v171, v134, v134
	global_store_dwordx4 v[178:179], v[132:135], off offset:512
	global_store_dwordx4 v[178:179], v[128:131], off offset:528
	v_mul_f32_e32 v173, v131, v131
	v_pk_mul_f32 v[142:143], v[80:81], v[128:129]
	v_fmac_f32_e32 v172, v128, v128
	v_add_f32_e32 v129, v170, v171
	v_fmac_f32_e32 v173, v130, v130
	v_add_f32_e32 v129, v129, v172
	v_add_f32_e32 v129, v173, v129
	v_pk_mul_f32 v[138:139], v[84:85], v[132:133]
	v_add_f32_e32 v132, v180, v129
	ds_swizzle_b32 v133, v132 offset:swizzle(SWAP,16)
	v_pk_mul_f32 v[136:137], v[86:87], v[134:135]
	v_pk_mul_f32 v[140:141], v[82:83], v[130:131]
	v_cvt_pk_bf16_f32 v128, v138, v139
	v_cvt_pk_bf16_f32 v129, v136, v137
	v_cvt_pk_bf16_f32 v130, v142, v143
	v_cvt_pk_bf16_f32 v131, v140, v141
	global_store_dwordx4 v[182:183], v[128:131], off offset:256
	s_waitcnt lgkmcnt(0)
	s_nop 0
	v_add_f32_e32 v128, v132, v133
	v_mov_b32_e32 v129, v128
	s_nop 1
	v_permlane32_swap_b32_e32 v128, v129
	s_and_saveexec_b64 s[8:9], s[4:5]
	s_cbranch_execz .LBB0_638
	v_lshl_add_u64 v[130:131], v[162:163], 2, s[28:29]
	v_add_f32_e32 v128, v128, v129
	global_atomic_add_f32 v[130:131], v128, off
.LBB0_638:
	s_or_b64 exec, exec, s[8:9]
	v_or_b32_e32 v128, 16, v162
	v_ashrrev_i32_e32 v129, 31, v128
	v_lshlrev_b64 v[130:131], 10, v[128:129]
	v_lshl_add_u64 v[130:131], v[130:131], 0, v[160:161]
	v_lshlrev_b64 v[138:139], 2, v[130:131]
	v_lshl_add_u64 v[140:141], s[16:17], 0, v[138:139]
	v_mov_b64_e32 v[142:143], s[18:19]
	v_mad_i64_i32 v[142:143], s[8:9], v128, s66, v[142:143]
	v_lshl_add_u64 v[142:143], v[160:161], 1, v[142:143]
	v_lshl_add_u64 v[138:139], s[12:13], 0, v[138:139]
	v_pk_add_f32 v[126:127], v[126:127], v[242:243]
	v_pk_add_f32 v[124:125], v[124:125], v[240:241]
	v_pk_add_f32 v[122:123], v[122:123], v[246:247]
	v_pk_add_f32 v[120:121], v[120:121], v[244:245]
	v_pk_mul_f32 v[132:133], v[94:95], v[126:127]
	v_pk_mul_f32 v[130:131], v[92:93], v[124:125]
	v_pk_mul_f32 v[134:135], v[90:91], v[122:123]
	v_pk_mul_f32 v[136:137], v[88:89], v[120:121]
	v_cvt_pk_bf16_f32 v130, v130, v131
	v_cvt_pk_bf16_f32 v131, v132, v133
	v_cvt_pk_bf16_f32 v132, v136, v137
	v_cvt_pk_bf16_f32 v133, v134, v135
	global_store_dwordx4 v[138:139], v[124:127], off
	global_store_dwordx4 v[138:139], v[120:123], off offset:16
	global_store_dwordx4 v[142:143], v[130:133], off
	global_load_dwordx4 v[130:133], v[140:141], off offset:512
	s_nop 0
	global_load_dwordx4 v[134:137], v[140:141], off offset:528
	v_mul_f32_e32 v125, v125, v125
	v_mul_f32_e32 v127, v127, v127
	v_mul_f32_e32 v121, v121, v121
	v_fmac_f32_e32 v125, v124, v124
	v_fmac_f32_e32 v127, v126, v126
	v_mul_f32_e32 v123, v123, v123
	v_fmac_f32_e32 v121, v120, v120
	v_add_f32_e32 v120, v125, v127
	v_fmac_f32_e32 v123, v122, v122
	v_add_f32_e32 v120, v120, v121
	v_add_f32_e32 v140, v123, v120
	s_waitcnt vmcnt(1)
	v_pk_add_f32 v[118:119], v[118:119], v[132:133]
	v_pk_add_f32 v[116:117], v[116:117], v[130:131]
	s_waitcnt vmcnt(0)
	v_pk_add_f32 v[112:113], v[112:113], v[134:135]
	v_mul_f32_e32 v130, v117, v117
	v_mul_f32_e32 v131, v119, v119
	v_pk_add_f32 v[114:115], v[114:115], v[136:137]
	v_mul_f32_e32 v132, v113, v113
	v_fmac_f32_e32 v130, v116, v116
	v_fmac_f32_e32 v131, v118, v118
	global_store_dwordx4 v[138:139], v[116:119], off offset:512
	global_store_dwordx4 v[138:139], v[112:115], off offset:528
	v_mul_f32_e32 v133, v115, v115
	v_pk_mul_f32 v[126:127], v[80:81], v[112:113]
	v_fmac_f32_e32 v132, v112, v112
	v_add_f32_e32 v113, v130, v131
	v_fmac_f32_e32 v133, v114, v114
	v_add_f32_e32 v113, v113, v132
	v_add_f32_e32 v113, v133, v113
	v_pk_mul_f32 v[122:123], v[84:85], v[116:117]
	v_add_f32_e32 v116, v140, v113
	ds_swizzle_b32 v117, v116 offset:swizzle(SWAP,16)
	v_pk_mul_f32 v[120:121], v[86:87], v[118:119]
	v_pk_mul_f32 v[124:125], v[82:83], v[114:115]
	v_cvt_pk_bf16_f32 v112, v122, v123
	v_cvt_pk_bf16_f32 v113, v120, v121
	v_cvt_pk_bf16_f32 v114, v126, v127
	v_cvt_pk_bf16_f32 v115, v124, v125
	global_store_dwordx4 v[142:143], v[112:115], off offset:256
	s_waitcnt lgkmcnt(0)
	s_nop 0
	v_add_f32_e32 v112, v116, v117
	v_mov_b32_e32 v113, v112
	s_nop 1
	v_permlane32_swap_b32_e32 v112, v113
	s_and_saveexec_b64 s[8:9], s[4:5]
	s_cbranch_execz .LBB0_640
	v_lshl_add_u64 v[114:115], v[128:129], 2, s[28:29]
	v_add_f32_e32 v112, v112, v113
	global_atomic_add_f32 v[114:115], v112, off
